# static s_setprio 1 for waves 4-7 at kernel entry (younger half of each 2-wave SIMD pair)
# speedup vs baseline: 1.0117x; 1.0047x over previous
; DI void hsync_impl(const bool INIT) {
;   __shared__ unsigned hb[4];
;   if (INIT) {
;     hb[0] = 0u; hb[1] = 0u; hb[2] = 0u; hb[3] = 0u;
;     return;
;   }
; __global__ void __launch_bounds__(512) fwd_megakernel(Params p) {
;   extern __shared__ __attribute__((aligned(16))) char smem[];
;   cg::grid_group grid = cg::this_grid();
;   __shared__ uint4 xb_words;
;   if (threadIdx.x == 0) {
;     xb_words = make_uint4(0u, 0u, 0u, 0u);
;     hsync_impl(true);
;   }
;   __syncthreads();
_Z14fwd_megakernel6Params:
	v_readfirstlane_b32 s3, v0
	s_nop 3
	s_and_b32 s3, s3, 0x3ff
	s_cmp_ge_u32 s3, 256
	s_cbranch_scc0 .Lprio_done
	s_setprio 1
.Lprio_done:
	s_load_dwordx16 s[72:87], s[0:1], 0x80
	s_load_dwordx2 s[54:55], s[0:1], 0xc0
	s_add_u32 s4, s0, 0xc0
	v_and_b32_e32 v211, 0x3ff, v0
	s_mov_b32 s52, s2
	s_addc_u32 s5, s1, 0
	s_mov_b32 s8, 0
	v_cmp_eq_u32_e64 s[58:59], 0, v211
	s_and_saveexec_b64 s[2:3], s[58:59]
	s_cbranch_execz .LBB0_2
	s_mov_b32 s9, s8
	s_mov_b32 s10, s8
	s_mov_b32 s11, s8
	v_mov_b64_e32 v[2:3], s[8:9]
	v_mov_b32_e32 v1, 0
	v_mov_b64_e32 v[4:5], s[10:11]
	ds_write_b128 v1, v[2:5] offset:16
	ds_write_b128 v1, v[2:5]
